# attention loop restructured: 32-key half-tile software pipeline in every wave (no skew), one barrier per tile pair placed after the LDS stores
# baseline (speedup 1.0000x reference)
; DEV void attn_item(const P& p, int bh, int qrow0, int nkt, int outrow0, char* smem) {
;     ...
;   int vo = 0; asm volatile("" : "+v"(vo));
;   bf16x8 qf[2][3];
; #pragma unroll
;   for (int qt = 0; qt < 2; ++qt)
; #pragma unroll
;     for (int ks = 0; ks < 3; ++ks) qf[qt][ks] = *(const bf16x8*)(Qb + (size_t)(qrow0 + wid * 32 + qt * 16 + l15) * 96 + ks * 32 + lq * 8);
;   f32x4 o[4][2];
; #pragma unroll
;   for (int vt = 0; vt < 4; ++vt)
; #pragma unroll
;     for (int qt = 0; qt < 2; ++qt) o[vt][qt] = (f32x4){0.f, 0.f, 0.f, 0.f};
;   float mused[2] = {0.f, 0.f};
;   f32x4 osum[2] = {(f32x4){0.f, 0.f, 0.f, 0.f}, (f32x4){0.f, 0.f, 0.f, 0.f}};
;   const bf16x8 ones = __builtin_bit_cast(bf16x8, (u32x4){0x3f803f80u, 0x3f803f80u, 0x3f803f80u, 0x3f803f80u});
;   u32x4 kr[4], vr[2];
;   const int krow = tid >> 4, kc = tid & 15;
;   const int vrow = tid >> 3, vc = tid & 7;
;   const int kwo = vo + krow * 256 + ((kc ^ (krow & 15)) << 4), vwo = vo + VBASE + vrow * 128 + ((vc ^ ((vrow >> 1) & 7)) << 4);
;   const int kro = vo + l15 * 256, vro = vo + VBASE + l15 * 128;
;   f32x4 st[4][2];
;   bf16x8 pf[2][2], vf[2][4];
.LBB0_158:
	s_waitcnt lgkmcnt(0)
	s_barrier
	s_cmpk_gt_u32 s6, 0xff
	v_lshrrev_b32_e32 v1, 1, v207
	v_lshl_add_u32 v210, v207, 7, v4
	s_cselect_b64 s[4:5], -1, 0
	s_cmp_lt_i32 s23, 1
	v_xor_b32_e32 v211, v206, v1
	v_bitop3_b32 v208, v206, v1, 4 bitop3:0x36
	s_cbranch_scc1 .LBB0_214
	v_mov_b32_e32 v1, v41
	v_lshl_add_u64 v[204:205], s[2:3], 0, v[0:1]
	v_xor_b32_e32 v0, v206, v207
	v_lshlrev_b32_e32 v217, 4, v0
	v_bitop3_b32 v0, v206, v207, 4 bitop3:0x36
	v_mov_b32_e32 v42, v41
	v_mov_b32_e32 v43, v41
	v_lshlrev_b32_e32 v218, 4, v0
	v_bitop3_b32 v0, v206, v207, 8 bitop3:0x36
	v_mov_b32_e32 v40, v41
	v_mov_b32_e32 v221, 0
	v_mov_b64_e32 v[94:95], v[42:43]
	v_mov_b64_e32 v[98:99], v[42:43]
	v_mov_b64_e32 v[102:103], v[42:43]
	v_mov_b64_e32 v[106:107], v[42:43]
	v_mov_b64_e32 v[110:111], v[42:43]
	v_mov_b64_e32 v[114:115], v[42:43]
	v_mov_b64_e32 v[118:119], v[42:43]
	v_mov_b64_e32 v[122:123], v[42:43]
	v_lshl_add_u32 v214, v207, 8, v2
	v_lshlrev_b32_e32 v215, 4, v211
	v_lshlrev_b32_e32 v216, 4, v208
	v_lshlrev_b32_e32 v219, 4, v0
	s_mov_b32 s25, 0
	v_mov_b32_e32 v220, 0
	v_mov_b64_e32 v[92:93], v[40:41]
	v_mov_b64_e32 v[96:97], v[40:41]
	v_mov_b64_e32 v[100:101], v[40:41]
	v_mov_b64_e32 v[104:105], v[40:41]
	v_mov_b64_e32 v[108:109], v[40:41]
	v_mov_b64_e32 v[112:113], v[40:41]
	v_mov_b64_e32 v[116:117], v[40:41]
	v_mov_b64_e32 v[120:121], v[40:41]
	s_mov_b32 s10, 0
	s_mov_b32 s11, 0
	v_mov_b32_e32 v0, 0
	v_mov_b32_e32 v1, v221
	v_mov_b32_e32 v2, v221
	v_mov_b32_e32 v3, v221
	v_mov_b32_e32 v4, v221
	v_mov_b32_e32 v5, v221
	v_mov_b32_e32 v6, v221
	v_mov_b32_e32 v7, v221
	v_xor_b32_e32 v226, 0x80000000, v221
	v_xor_b32_e32 v230, 0x80000000, v220
	v_mov_b32_e32 v222, s56
	v_mov_b32_e32 v227, v226
	v_mov_b32_e32 v231, v230
	v_mov_b32_e32 v223, v222
	v_mov_b32_e32 v228, v226
	v_mov_b32_e32 v232, v230
	v_mov_b32_e32 v224, v222
	v_mov_b32_e32 v229, v226
	v_mov_b32_e32 v233, v230
	v_mov_b32_e32 v225, v222
	v_mov_b32_e32 v16, 0
	v_mov_b32_e32 v17, 0
	v_mov_b32_e32 v18, 0
	v_mov_b32_e32 v19, 0
	v_mov_b32_e32 v20, 0
	v_mov_b32_e32 v21, 0
	v_mov_b32_e32 v22, 0
	v_mov_b32_e32 v23, 0
	v_mov_b32_e32 v24, 0
	v_mov_b32_e32 v25, 0
	v_mov_b32_e32 v26, 0
	v_mov_b32_e32 v27, 0
	v_mov_b32_e32 v28, 0
	v_mov_b32_e32 v29, 0
	v_mov_b32_e32 v30, 0
	v_mov_b32_e32 v31, 0
	v_mov_b32_e32 v148, 0
	v_mov_b32_e32 v149, 0
	v_mov_b32_e32 v150, 0
	v_mov_b32_e32 v151, 0
	v_mov_b32_e32 v132, 0
	v_mov_b32_e32 v133, 0
	v_mov_b32_e32 v134, 0
	v_mov_b32_e32 v135, 0
	v_lshl_add_u32 v8, s10, 14, v214
	v_add_u32_e32 v32, v8, v217
	v_add_u32_e32 v33, v8, v218
	v_add_u32_e32 v34, v8, v219
	ds_read_b128 v[156:159], v32 offset:0
	ds_read_b128 v[160:163], v32 offset:4096
	ds_read_b128 v[164:167], v33 offset:0
	ds_read_b128 v[168:171], v33 offset:4096
	ds_read_b128 v[172:175], v34 offset:0
	ds_read_b128 v[176:179], v34 offset:4096
	ds_read_b128 v[180:183], v32 offset:8192
	ds_read_b128 v[184:187], v32 offset:12288
	ds_read_b128 v[188:191], v33 offset:8192
	ds_read_b128 v[192:195], v33 offset:12288
	ds_read_b128 v[196:199], v34 offset:8192
	ds_read_b128 v[12:15], v34 offset:12288
	s_waitcnt lgkmcnt(6)
	v_mfma_f32_16x16x32_bf16 v[140:143], v[156:159], v[44:47], v[226:229]
	v_mfma_f32_16x16x32_bf16 v[124:127], v[156:159], v[56:59], v[230:233]
	v_mfma_f32_16x16x32_bf16 v[144:147], v[160:163], v[44:47], v[226:229]
	v_mfma_f32_16x16x32_bf16 v[128:131], v[160:163], v[56:59], v[230:233]
	v_mfma_f32_16x16x32_bf16 v[140:143], v[164:167], v[48:51], v[140:143]
	v_mfma_f32_16x16x32_bf16 v[124:127], v[164:167], v[60:63], v[124:127]
	v_mfma_f32_16x16x32_bf16 v[144:147], v[168:171], v[48:51], v[144:147]
	v_mfma_f32_16x16x32_bf16 v[128:131], v[168:171], v[60:63], v[128:131]
	v_mfma_f32_16x16x32_bf16 v[140:143], v[172:175], v[52:55], v[140:143]
	v_mfma_f32_16x16x32_bf16 v[124:127], v[172:175], v[64:67], v[124:127]
	v_mfma_f32_16x16x32_bf16 v[144:147], v[176:179], v[52:55], v[144:147]
	v_mfma_f32_16x16x32_bf16 v[128:131], v[176:179], v[64:67], v[128:131]

.Latt_h164:
	s_add_i32 s2, s11, 2
	s_cmp_ge_i32 s2, s23
	s_cbranch_scc1 .Latt_h168
	s_and_saveexec_b64 s[2:3], s[38:39]
	s_cbranch_execz .Latt_h167
	v_add_u32_e32 v43, s25, v209
	v_add_u32_e32 v8, 0x100, v43
	s_movk_i32 s8, 0xc0
	v_mad_i64_i32 v[8:9], s[6:7], v8, s8, v[204:205]
	v_add_u32_e32 v10, 0x120, v43
	v_mad_i64_i32 v[10:11], s[6:7], v10, s8, v[204:205]
	global_load_dwordx4 v[68:71], v[8:9], off
	global_load_dwordx4 v[72:75], v[10:11], off
	v_add_u32_e32 v8, 0x140, v43
	v_mad_i64_i32 v[8:9], s[6:7], v8, s8, v[204:205]
	v_add_u32_e32 v10, 0x160, v43
	v_mad_i64_i32 v[10:11], s[6:7], v10, s8, v[204:205]
	global_load_dwordx4 v[76:79], v[8:9], off
	global_load_dwordx4 v[80:83], v[10:11], off

; DEV int vbsel() { return __builtin_amdgcn_readfirstlane((int)(threadIdx.x >> 8)); }
; #define ALOAD(kt) { const int key0_ = (kt) * 128; \
;     if (kc < 12) { _Pragma("unroll") for (int i = 0; i < 4; ++i) kr[i] = *(const u32x4*)(Kb + (size_t)(key0_ + krow + 32 * i) * 96 + kc * 8); } \
;     _Pragma("unroll") for (int i = 0; i < 2; ++i) vr[i] = *(const u32x4*)(Vt + (size_t)vrow * NKEY + key0_ + i * 64 + vc * 8); }
; #define ASTORE(slot) { char* sk_ = smem + (slot) * KB; char* sv_ = smem + (slot) * VB; \
;     if (kc < 12) { _Pragma("unroll") for (int i = 0; i < 4; ++i) *(u32x4*)(sk_ + kwo + i * 8192) = kr[i]; } \
;     _Pragma("unroll") for (int i = 0; i < 2; ++i) *(u32x4*)(sv_ + vwo + i * VB) = vr[i]; }
; #define PVLOAD(slot) { const char* s = smem + (slot) * VB; \
;     _Pragma("unroll") for (int vt = 0; vt < 4; ++vt) vf[0][vt] = *(const bf16x8*)(s + vt * 2048 + vro + (((0 * 4 + lq) ^ (l15 >> 1)) << 4)); }
; #define ABAR() { asm volatile("s_waitcnt lgkmcnt(0)" ::: "memory"); __builtin_amdgcn_s_barrier(); asm volatile("" ::: "memory"); }
; DEV void attn_item(const P& p, int bh, int qrow0, int nkt, int outrow0, char* smem) {
;     ...
;   const bool skew = vbsel() != 0;
;   asm volatile("" : "+s"(nkt));
;     ...
;   const int npair = nkt >> 1;
;   ALOAD(0); ASTORE(0); if (npair > 1) ALOAD(1); ABAR();
;   int s0 = 0;
; #pragma nounroll
;   for (int kp = 0; kp < npair; ++kp) {
;     const int sn = (s0 == 4) ? 0 : s0 + 2;
;     if (kp + 1 < npair) ASTORE(sn);
;     if (kp + 2 < npair) ALOAD(kp + 2);
;     if (!skew) {
;       QK(s0); PVLOAD(s0); __builtin_amdgcn_sched_barrier(0); SM(kp == 0); PVMMA(s0);
;       QK(s0 + 1); PVLOAD(s0 + 1); __builtin_amdgcn_sched_barrier(0); SM(false); PVMMA(s0 + 1);
;     } else {
;       if (kp > 0) { const int sp = (s0 == 0) ? 5 : s0 - 1; PVLOAD(sp); __builtin_amdgcn_sched_barrier(0); SM(false); PVMMA(sp); }
;       QK(s0);
;       PVLOAD(s0); __builtin_amdgcn_sched_barrier(0); SM(kp == 0); PVMMA(s0);
;       QK(s0 + 1);
;     }
;     ABAR();
;     s0 = sn;
;   }
.Latt_h168:
	v_lshl_add_u32 v8, s10, 14, v214
	v_add_u32_e32 v32, v8, v217
	v_add_u32_e32 v33, v8, v218
	v_add_u32_e32 v34, v8, v219
	v_lshl_add_u32 v8, s24, 14, v214
	v_add_u32_e32 v35, v8, v217
	v_add_u32_e32 v36, v8, v218
	v_add_u32_e32 v37, v8, v219
	s_lshl_b32 s27, s10, 13
	v_add_u32_e32 v8, s27, v210
	v_add_u32_e32 v38, v8, v215
	v_add_u32_e32 v39, v8, v216
	s_waitcnt lgkmcnt(0)
	s_barrier
	s_waitcnt lgkmcnt(6)
	v_mfma_f32_16x16x32_bf16 v[92:95], v[16:19], v[148:151], v[92:95]
	v_mfma_f32_16x16x32_bf16 v[96:99], v[16:19], v[132:135], v[96:99]
	v_mfma_f32_16x16x32_bf16 v[100:103], v[20:23], v[148:151], v[100:103]
	v_mfma_f32_16x16x32_bf16 v[104:107], v[20:23], v[132:135], v[104:107]
	v_mfma_f32_16x16x32_bf16 v[108:111], v[24:27], v[148:151], v[108:111]
	v_mfma_f32_16x16x32_bf16 v[112:115], v[24:27], v[132:135], v[112:115]
	v_max3_f32 v40, v140, v141, v142
	v_max3_f32 v42, v124, v125, v126
	v_mfma_f32_16x16x32_bf16 v[116:119], v[28:31], v[148:151], v[116:119]
	v_max3_f32 v40, v40, v143, v144
	v_max3_f32 v42, v42, v127, v128
	v_mfma_f32_16x16x32_bf16 v[120:123], v[28:31], v[132:135], v[120:123]
	v_max3_f32 v40, v40, v145, v146
	v_max3_f32 v42, v42, v129, v130
	v_mfma_f32_16x16x32_bf16 v[0:3], v[222:225], v[148:151], v[0:3]
	v_max3_f32 v40, v40, v147, v147
	v_max3_f32 v42, v42, v131, v131
	v_mfma_f32_16x16x32_bf16 v[4:7], v[222:225], v[132:135], v[4:7]
	v_max_f32_e32 v9, v40, v42
	v_cmp_lt_f32_e32 vcc, s44, v9
	s_cmp_eq_u32 s11, 0
	s_cbranch_scc1 .Latt_rare_s0
	s_cbranch_vccnz .Latt_rare_s0
.Latt_c_s0:
	s_waitcnt lgkmcnt(0)
	v_mfma_f32_16x16x32_bf16 v[148:151], v[180:183], v[44:47], v[226:229]
	ds_read_b128 v[16:19], v38 offset:0
	v_exp_f32_e32 v140, v140
	v_exp_f32_e32 v141, v141
	v_exp_f32_e32 v142, v142
	v_mfma_f32_16x16x32_bf16 v[132:135], v[180:183], v[56:59], v[230:233]
	ds_read_b128 v[20:23], v38 offset:2048
	v_exp_f32_e32 v143, v143
	v_exp_f32_e32 v144, v144
	v_exp_f32_e32 v145, v145
	v_mfma_f32_16x16x32_bf16 v[152:155], v[184:187], v[44:47], v[226:229]
	ds_read_b128 v[24:27], v38 offset:4096
	v_exp_f32_e32 v146, v146
	v_exp_f32_e32 v147, v147
	v_mfma_f32_16x16x32_bf16 v[136:139], v[184:187], v[56:59], v[230:233]
	ds_read_b128 v[28:31], v38 offset:6144
	v_cvt_pk_bf16_f32 v140, v140, v141
	v_cvt_pk_bf16_f32 v141, v142, v143
	v_mfma_f32_16x16x32_bf16 v[148:151], v[188:191], v[48:51], v[148:151]
	ds_read_b128 v[156:159], v32 offset:16384
	v_cvt_pk_bf16_f32 v142, v144, v145
	v_cvt_pk_bf16_f32 v143, v146, v147
	v_mfma_f32_16x16x32_bf16 v[132:135], v[188:191], v[60:63], v[132:135]
	ds_read_b128 v[160:163], v32 offset:20480
	v_exp_f32_e32 v124, v124
	v_exp_f32_e32 v125, v125
	v_mfma_f32_16x16x32_bf16 v[152:155], v[192:195], v[48:51], v[152:155]
	ds_read_b128 v[164:167], v33 offset:16384
	v_exp_f32_e32 v126, v126
	v_exp_f32_e32 v127, v127
	v_mfma_f32_16x16x32_bf16 v[136:139], v[192:195], v[60:63], v[136:139]
	ds_read_b128 v[168:171], v33 offset:20480
	v_exp_f32_e32 v128, v128
	v_exp_f32_e32 v129, v129
	v_mfma_f32_16x16x32_bf16 v[148:151], v[196:199], v[52:55], v[148:151]
	ds_read_b128 v[172:175], v34 offset:16384
	v_exp_f32_e32 v130, v130
	v_exp_f32_e32 v131, v131
	v_mfma_f32_16x16x32_bf16 v[132:135], v[196:199], v[64:67], v[132:135]
	ds_read_b128 v[176:179], v34 offset:20480
	v_cvt_pk_bf16_f32 v124, v124, v125
	v_cvt_pk_bf16_f32 v125, v126, v127
	v_mfma_f32_16x16x32_bf16 v[152:155], v[12:15], v[52:55], v[152:155]
	v_cvt_pk_bf16_f32 v126, v128, v129
	v_cvt_pk_bf16_f32 v127, v130, v131
	v_mfma_f32_16x16x32_bf16 v[136:139], v[12:15], v[64:67], v[136:139]
	s_nop 1
	s_waitcnt lgkmcnt(6)
	v_mfma_f32_16x16x32_bf16 v[92:95], v[16:19], v[140:143], v[92:95]
	v_mfma_f32_16x16x32_bf16 v[96:99], v[16:19], v[124:127], v[96:99]
	v_mfma_f32_16x16x32_bf16 v[100:103], v[20:23], v[140:143], v[100:103]
	v_mfma_f32_16x16x32_bf16 v[104:107], v[20:23], v[124:127], v[104:107]
	v_mfma_f32_16x16x32_bf16 v[108:111], v[24:27], v[140:143], v[108:111]
	v_mfma_f32_16x16x32_bf16 v[112:115], v[24:27], v[124:127], v[112:115]
	v_max3_f32 v40, v148, v149, v150
	v_max3_f32 v42, v132, v133, v134
	v_mfma_f32_16x16x32_bf16 v[116:119], v[28:31], v[140:143], v[116:119]
	v_max3_f32 v40, v40, v151, v152
	v_max3_f32 v42, v42, v135, v136
	v_mfma_f32_16x16x32_bf16 v[120:123], v[28:31], v[124:127], v[120:123]
	v_max3_f32 v40, v40, v153, v154
	v_max3_f32 v42, v42, v137, v138
	v_mfma_f32_16x16x32_bf16 v[0:3], v[222:225], v[140:143], v[0:3]
	v_max3_f32 v40, v40, v155, v155
	v_max3_f32 v42, v42, v139, v139
	v_mfma_f32_16x16x32_bf16 v[4:7], v[222:225], v[124:127], v[4:7]
	v_max_f32_e32 v9, v40, v42
	v_cmp_lt_f32_e32 vcc, s44, v9
	s_cbranch_vccnz .Latt_rare_s1
.Latt_c_s1:
	s_waitcnt lgkmcnt(0)
	v_mfma_f32_16x16x32_bf16 v[140:143], v[156:159], v[44:47], v[226:229]
	ds_read_b128 v[16:19], v39 offset:0
	v_exp_f32_e32 v148, v148
	v_exp_f32_e32 v149, v149
	v_exp_f32_e32 v150, v150
	v_mfma_f32_16x16x32_bf16 v[124:127], v[156:159], v[56:59], v[230:233]
	ds_read_b128 v[20:23], v39 offset:2048
	v_exp_f32_e32 v151, v151
	v_exp_f32_e32 v152, v152
	v_exp_f32_e32 v153, v153
	v_mfma_f32_16x16x32_bf16 v[144:147], v[160:163], v[44:47], v[226:229]
	ds_read_b128 v[24:27], v39 offset:4096
	v_exp_f32_e32 v154, v154
	v_exp_f32_e32 v155, v155
	v_mfma_f32_16x16x32_bf16 v[128:131], v[160:163], v[56:59], v[230:233]
	ds_read_b128 v[28:31], v39 offset:6144
	v_cvt_pk_bf16_f32 v148, v148, v149
	v_cvt_pk_bf16_f32 v149, v150, v151
	v_mfma_f32_16x16x32_bf16 v[140:143], v[164:167], v[48:51], v[140:143]
	ds_read_b128 v[180:183], v32 offset:24576
	v_cvt_pk_bf16_f32 v150, v152, v153
	v_cvt_pk_bf16_f32 v151, v154, v155
	v_mfma_f32_16x16x32_bf16 v[124:127], v[164:167], v[60:63], v[124:127]
	ds_read_b128 v[184:187], v32 offset:28672
	v_exp_f32_e32 v132, v132
	v_exp_f32_e32 v133, v133
	v_mfma_f32_16x16x32_bf16 v[144:147], v[168:171], v[48:51], v[144:147]
	ds_read_b128 v[188:191], v33 offset:24576
	v_exp_f32_e32 v134, v134
	v_exp_f32_e32 v135, v135
	v_mfma_f32_16x16x32_bf16 v[128:131], v[168:171], v[60:63], v[128:131]
	ds_read_b128 v[192:195], v33 offset:28672
	v_exp_f32_e32 v136, v136
	v_exp_f32_e32 v137, v137
	v_mfma_f32_16x16x32_bf16 v[140:143], v[172:175], v[52:55], v[140:143]
	ds_read_b128 v[196:199], v34 offset:24576
	v_exp_f32_e32 v138, v138
	v_exp_f32_e32 v139, v139
	v_mfma_f32_16x16x32_bf16 v[124:127], v[172:175], v[64:67], v[124:127]
	ds_read_b128 v[12:15], v34 offset:28672
	v_cvt_pk_bf16_f32 v132, v132, v133
	v_cvt_pk_bf16_f32 v133, v134, v135
	v_mfma_f32_16x16x32_bf16 v[144:147], v[176:179], v[52:55], v[144:147]
	v_cvt_pk_bf16_f32 v134, v136, v137
	v_cvt_pk_bf16_f32 v135, v138, v139
	v_mfma_f32_16x16x32_bf16 v[128:131], v[176:179], v[64:67], v[128:131]
	s_nop 1
	s_waitcnt lgkmcnt(6)
	v_mfma_f32_16x16x32_bf16 v[92:95], v[16:19], v[148:151], v[92:95]
	v_mfma_f32_16x16x32_bf16 v[96:99], v[16:19], v[132:135], v[96:99]
	v_mfma_f32_16x16x32_bf16 v[100:103], v[20:23], v[148:151], v[100:103]
	v_mfma_f32_16x16x32_bf16 v[104:107], v[20:23], v[132:135], v[104:107]
	v_mfma_f32_16x16x32_bf16 v[108:111], v[24:27], v[148:151], v[108:111]
	v_mfma_f32_16x16x32_bf16 v[112:115], v[24:27], v[132:135], v[112:115]
	v_max3_f32 v40, v140, v141, v142
	v_max3_f32 v42, v124, v125, v126
	v_mfma_f32_16x16x32_bf16 v[116:119], v[28:31], v[148:151], v[116:119]
	v_max3_f32 v40, v40, v143, v144
	v_max3_f32 v42, v42, v127, v128
	v_mfma_f32_16x16x32_bf16 v[120:123], v[28:31], v[132:135], v[120:123]
	v_max3_f32 v40, v40, v145, v146
	v_max3_f32 v42, v42, v129, v130
	v_mfma_f32_16x16x32_bf16 v[0:3], v[222:225], v[148:151], v[0:3]
	v_max3_f32 v40, v40, v147, v147
	v_max3_f32 v42, v42, v131, v131
	v_mfma_f32_16x16x32_bf16 v[4:7], v[222:225], v[132:135], v[4:7]
	v_max_f32_e32 v9, v40, v42
	v_cmp_lt_f32_e32 vcc, s44, v9
	s_cbranch_vccnz .Latt_rare_s2
.Latt_c_s2:
	s_waitcnt lgkmcnt(0)
	v_mfma_f32_16x16x32_bf16 v[148:151], v[180:183], v[44:47], v[226:229]
	ds_read_b128 v[16:19], v38 offset:8192
	v_exp_f32_e32 v140, v140
	v_exp_f32_e32 v141, v141
	v_exp_f32_e32 v142, v142
	v_mfma_f32_16x16x32_bf16 v[132:135], v[180:183], v[56:59], v[230:233]
	ds_read_b128 v[20:23], v38 offset:10240
	v_exp_f32_e32 v143, v143
	v_exp_f32_e32 v144, v144
	v_exp_f32_e32 v145, v145
	v_mfma_f32_16x16x32_bf16 v[152:155], v[184:187], v[44:47], v[226:229]
	ds_read_b128 v[24:27], v38 offset:12288
	v_exp_f32_e32 v146, v146
	v_exp_f32_e32 v147, v147
	v_mfma_f32_16x16x32_bf16 v[136:139], v[184:187], v[56:59], v[230:233]
	ds_read_b128 v[28:31], v38 offset:14336
	v_cvt_pk_bf16_f32 v140, v140, v141
	v_cvt_pk_bf16_f32 v141, v142, v143
	v_mfma_f32_16x16x32_bf16 v[148:151], v[188:191], v[48:51], v[148:151]
	ds_read_b128 v[156:159], v35 offset:0
	v_cvt_pk_bf16_f32 v142, v144, v145
	v_cvt_pk_bf16_f32 v143, v146, v147
	v_mfma_f32_16x16x32_bf16 v[132:135], v[188:191], v[60:63], v[132:135]
	ds_read_b128 v[160:163], v35 offset:4096
	v_exp_f32_e32 v124, v124
	v_exp_f32_e32 v125, v125
	v_mfma_f32_16x16x32_bf16 v[152:155], v[192:195], v[48:51], v[152:155]
	ds_read_b128 v[164:167], v36 offset:0
	v_exp_f32_e32 v126, v126
	v_exp_f32_e32 v127, v127
	v_mfma_f32_16x16x32_bf16 v[136:139], v[192:195], v[60:63], v[136:139]
	ds_read_b128 v[168:171], v36 offset:4096
	v_exp_f32_e32 v128, v128
	v_exp_f32_e32 v129, v129
	v_mfma_f32_16x16x32_bf16 v[148:151], v[196:199], v[52:55], v[148:151]
	ds_read_b128 v[172:175], v37 offset:0
	v_exp_f32_e32 v130, v130
	v_exp_f32_e32 v131, v131
	v_mfma_f32_16x16x32_bf16 v[132:135], v[196:199], v[64:67], v[132:135]
	ds_read_b128 v[176:179], v37 offset:4096
	v_cvt_pk_bf16_f32 v124, v124, v125
	v_cvt_pk_bf16_f32 v125, v126, v127
	v_mfma_f32_16x16x32_bf16 v[152:155], v[12:15], v[52:55], v[152:155]
	v_cvt_pk_bf16_f32 v126, v128, v129
	v_cvt_pk_bf16_f32 v127, v130, v131
	v_mfma_f32_16x16x32_bf16 v[136:139], v[12:15], v[64:67], v[136:139]
	s_nop 1
	s_waitcnt lgkmcnt(6)
	v_mfma_f32_16x16x32_bf16 v[92:95], v[16:19], v[140:143], v[92:95]
	v_mfma_f32_16x16x32_bf16 v[96:99], v[16:19], v[124:127], v[96:99]
	v_mfma_f32_16x16x32_bf16 v[100:103], v[20:23], v[140:143], v[100:103]
	v_mfma_f32_16x16x32_bf16 v[104:107], v[20:23], v[124:127], v[104:107]
	v_mfma_f32_16x16x32_bf16 v[108:111], v[24:27], v[140:143], v[108:111]
	v_mfma_f32_16x16x32_bf16 v[112:115], v[24:27], v[124:127], v[112:115]
	v_max3_f32 v40, v148, v149, v150
	v_max3_f32 v42, v132, v133, v134
	v_mfma_f32_16x16x32_bf16 v[116:119], v[28:31], v[140:143], v[116:119]
	v_max3_f32 v40, v40, v151, v152
	v_max3_f32 v42, v42, v135, v136
	v_mfma_f32_16x16x32_bf16 v[120:123], v[28:31], v[124:127], v[120:123]
	v_max3_f32 v40, v40, v153, v154
	v_max3_f32 v42, v42, v137, v138
	v_mfma_f32_16x16x32_bf16 v[0:3], v[222:225], v[140:143], v[0:3]
	v_max3_f32 v40, v40, v155, v155
	v_max3_f32 v42, v42, v139, v139
	v_mfma_f32_16x16x32_bf16 v[4:7], v[222:225], v[124:127], v[4:7]
	v_max_f32_e32 v9, v40, v42
	v_cmp_lt_f32_e32 vcc, s44, v9
	s_cbranch_vccnz .Latt_rare_s3
; DEV int vbsel() { return __builtin_amdgcn_readfirstlane((int)(threadIdx.x >> 8)); }
; #define ALOAD(kt) { const int key0_ = (kt) * 128; \
;     if (kc < 12) { _Pragma("unroll") for (int i = 0; i < 4; ++i) kr[i] = *(const u32x4*)(Kb + (size_t)(key0_ + krow + 32 * i) * 96 + kc * 8); } \
;     _Pragma("unroll") for (int i = 0; i < 2; ++i) vr[i] = *(const u32x4*)(Vt + (size_t)vrow * NKEY + key0_ + i * 64 + vc * 8); }
; #define ASTORE(slot) { char* sk_ = smem + (slot) * KB; char* sv_ = smem + (slot) * VB; \
;     if (kc < 12) { _Pragma("unroll") for (int i = 0; i < 4; ++i) *(u32x4*)(sk_ + kwo + i * 8192) = kr[i]; } \
;     _Pragma("unroll") for (int i = 0; i < 2; ++i) *(u32x4*)(sv_ + vwo + i * VB) = vr[i]; }
; #define PVLOAD(slot) { const char* s = smem + (slot) * VB; \
;     _Pragma("unroll") for (int vt = 0; vt < 4; ++vt) vf[0][vt] = *(const bf16x8*)(s + vt * 2048 + vro + (((0 * 4 + lq) ^ (l15 >> 1)) << 4)); }
; #define ABAR() { asm volatile("s_waitcnt lgkmcnt(0)" ::: "memory"); __builtin_amdgcn_s_barrier(); asm volatile("" ::: "memory"); }
; DEV void attn_item(const P& p, int bh, int qrow0, int nkt, int outrow0, char* smem) {
;     ...
;   const bool skew = vbsel() != 0;
;   asm volatile("" : "+s"(nkt));
;     ...
;   const int npair = nkt >> 1;
;   ALOAD(0); ASTORE(0); if (npair > 1) ALOAD(1); ABAR();
;   int s0 = 0;
; #pragma nounroll
;   for (int kp = 0; kp < npair; ++kp) {
;     const int sn = (s0 == 4) ? 0 : s0 + 2;
;     if (kp + 1 < npair) ASTORE(sn);
;     if (kp + 2 < npair) ALOAD(kp + 2);
;     if (!skew) {
;       QK(s0); PVLOAD(s0); __builtin_amdgcn_sched_barrier(0); SM(kp == 0); PVMMA(s0);
;       QK(s0 + 1); PVLOAD(s0 + 1); __builtin_amdgcn_sched_barrier(0); SM(false); PVMMA(s0 + 1);
;     } else {
;       if (kp > 0) { const int sp = (s0 == 0) ? 5 : s0 - 1; PVLOAD(sp); __builtin_amdgcn_sched_barrier(0); SM(false); PVMMA(sp); }
;       QK(s0);
;       PVLOAD(s0); __builtin_amdgcn_sched_barrier(0); SM(kp == 0); PVMMA(s0);
;       QK(s0 + 1);
;     }
;     ABAR();
;     s0 = sn;
.Latt_c_s3:
	s_waitcnt lgkmcnt(0)
	v_mfma_f32_16x16x32_bf16 v[140:143], v[156:159], v[44:47], v[226:229]
	ds_read_b128 v[16:19], v39 offset:8192
	v_exp_f32_e32 v148, v148
	v_exp_f32_e32 v149, v149
	v_exp_f32_e32 v150, v150
	v_mfma_f32_16x16x32_bf16 v[124:127], v[156:159], v[56:59], v[230:233]
	ds_read_b128 v[20:23], v39 offset:10240
	v_exp_f32_e32 v151, v151
	v_exp_f32_e32 v152, v152
	v_exp_f32_e32 v153, v153
	v_mfma_f32_16x16x32_bf16 v[144:147], v[160:163], v[44:47], v[226:229]
	ds_read_b128 v[24:27], v39 offset:12288
	v_exp_f32_e32 v154, v154
	v_exp_f32_e32 v155, v155
	v_mfma_f32_16x16x32_bf16 v[128:131], v[160:163], v[56:59], v[230:233]
	ds_read_b128 v[28:31], v39 offset:14336
	v_cvt_pk_bf16_f32 v148, v148, v149
	v_cvt_pk_bf16_f32 v149, v150, v151
	v_mfma_f32_16x16x32_bf16 v[140:143], v[164:167], v[48:51], v[140:143]
	ds_read_b128 v[180:183], v35 offset:8192
	v_cvt_pk_bf16_f32 v150, v152, v153
	v_cvt_pk_bf16_f32 v151, v154, v155
	v_mfma_f32_16x16x32_bf16 v[124:127], v[164:167], v[60:63], v[124:127]
	ds_read_b128 v[184:187], v35 offset:12288
	v_exp_f32_e32 v132, v132
	v_exp_f32_e32 v133, v133
	v_mfma_f32_16x16x32_bf16 v[144:147], v[168:171], v[48:51], v[144:147]
	ds_read_b128 v[188:191], v36 offset:8192
	v_exp_f32_e32 v134, v134
	v_exp_f32_e32 v135, v135
	v_mfma_f32_16x16x32_bf16 v[128:131], v[168:171], v[60:63], v[128:131]
	ds_read_b128 v[192:195], v36 offset:12288
	v_exp_f32_e32 v136, v136
	v_exp_f32_e32 v137, v137
	v_mfma_f32_16x16x32_bf16 v[140:143], v[172:175], v[52:55], v[140:143]
	ds_read_b128 v[196:199], v37 offset:8192
	v_exp_f32_e32 v138, v138
	v_exp_f32_e32 v139, v139
	v_mfma_f32_16x16x32_bf16 v[124:127], v[172:175], v[64:67], v[124:127]
	ds_read_b128 v[12:15], v37 offset:12288
	v_cvt_pk_bf16_f32 v132, v132, v133
	v_cvt_pk_bf16_f32 v133, v134, v135
	v_mfma_f32_16x16x32_bf16 v[144:147], v[176:179], v[52:55], v[144:147]
	v_cvt_pk_bf16_f32 v134, v136, v137
	v_cvt_pk_bf16_f32 v135, v138, v139
	v_mfma_f32_16x16x32_bf16 v[128:131], v[176:179], v[64:67], v[128:131]
	s_nop 1
	s_addk_i32 s25, 0x80
	s_cmp_eq_u32 s23, s26
	s_cbranch_scc1 .Latt_exit
	s_mov_b32 s10, s24
	s_mov_b32 s11, s26
	s_branch .Latt_loop
.Latt_rare_s0:
	s_nop 7
	s_cmp_eq_u32 s11, 0
	s_cbranch_scc1 .Latt_r0_s0
	v_cmp_lt_f32_e32 vcc, s44, v40
	s_cbranch_vccz .Latt_r1chk_s0
.Latt_r0_s0:
	v_xor_b32_e32 v10, 16, v237
	v_lshlrev_b32_e32 v10, 2, v10
	ds_bpermute_b32 v10, v10, v40
	v_xor_b32_e32 v43, 32, v237
	v_lshlrev_b32_e32 v43, 2, v43
	v_max_f32_e32 v11, v40, v40
	s_waitcnt lgkmcnt(0)
	v_max_f32_e32 v10, v10, v10
	v_max_f32_e32 v11, v11, v10
	s_nop 0
	ds_bpermute_b32 v10, v43, v11
	s_waitcnt lgkmcnt(0)
	v_max_f32_e32 v10, v10, v10
	v_max_f32_e32 v11, v11, v10
	v_exp_f32_e64 v8, -v11
	v_add_f32_e32 v221, v221, v11
	v_xor_b32_e32 v226, 0x80000000, v221
	v_sub_f32_e32 v140, v140, v11
	v_sub_f32_e32 v141, v141, v11
	v_sub_f32_e32 v142, v142, v11
	v_sub_f32_e32 v143, v143, v11
	v_sub_f32_e32 v144, v144, v11
	v_sub_f32_e32 v145, v145, v11
	v_sub_f32_e32 v146, v146, v11
	v_sub_f32_e32 v147, v147, v11
	v_mov_b32_e32 v227, v226
	v_mov_b32_e32 v228, v226
	v_mov_b32_e32 v229, v226
	v_pk_mul_f32 v[92:93], v[92:93], v[8:9] op_sel_hi:[1,0]
	v_pk_mul_f32 v[94:95], v[94:95], v[8:9] op_sel_hi:[1,0]
	v_pk_mul_f32 v[100:101], v[100:101], v[8:9] op_sel_hi:[1,0]
	v_pk_mul_f32 v[102:103], v[102:103], v[8:9] op_sel_hi:[1,0]
	v_pk_mul_f32 v[108:109], v[108:109], v[8:9] op_sel_hi:[1,0]
	v_pk_mul_f32 v[110:111], v[110:111], v[8:9] op_sel_hi:[1,0]
	v_pk_mul_f32 v[116:117], v[116:117], v[8:9] op_sel_hi:[1,0]
	v_pk_mul_f32 v[118:119], v[118:119], v[8:9] op_sel_hi:[1,0]
	v_pk_mul_f32 v[0:1], v[0:1], v[8:9] op_sel_hi:[1,0]
	v_pk_mul_f32 v[2:3], v[2:3], v[8:9] op_sel_hi:[1,0]
.Latt_r1chk_s0:
	s_cmp_eq_u32 s11, 0
	s_cbranch_scc1 .Latt_r1_s0
	v_cmp_lt_f32_e32 vcc, s44, v42
	s_cbranch_vccz .Latt_c_s0
.Latt_r1_s0:
	v_xor_b32_e32 v10, 16, v237
	v_lshlrev_b32_e32 v10, 2, v10
	ds_bpermute_b32 v10, v10, v42
	v_xor_b32_e32 v43, 32, v237
	v_lshlrev_b32_e32 v43, 2, v43
	v_max_f32_e32 v11, v42, v42
	s_waitcnt lgkmcnt(0)
	v_max_f32_e32 v10, v10, v10
	v_max_f32_e32 v11, v11, v10
	s_nop 0
	ds_bpermute_b32 v10, v43, v11
	s_waitcnt lgkmcnt(0)
	v_max_f32_e32 v10, v10, v10
	v_max_f32_e32 v11, v11, v10
	v_exp_f32_e64 v8, -v11
	v_add_f32_e32 v220, v220, v11
	v_xor_b32_e32 v230, 0x80000000, v220
	v_sub_f32_e32 v124, v124, v11
	v_sub_f32_e32 v125, v125, v11
	v_sub_f32_e32 v126, v126, v11
	v_sub_f32_e32 v127, v127, v11
	v_sub_f32_e32 v128, v128, v11
	v_sub_f32_e32 v129, v129, v11
	v_sub_f32_e32 v130, v130, v11
	v_sub_f32_e32 v131, v131, v11
	v_mov_b32_e32 v231, v230
	v_mov_b32_e32 v232, v230
	v_mov_b32_e32 v233, v230
	v_pk_mul_f32 v[96:97], v[96:97], v[8:9] op_sel_hi:[1,0]
	v_pk_mul_f32 v[98:99], v[98:99], v[8:9] op_sel_hi:[1,0]
	v_pk_mul_f32 v[104:105], v[104:105], v[8:9] op_sel_hi:[1,0]
	v_pk_mul_f32 v[106:107], v[106:107], v[8:9] op_sel_hi:[1,0]
	v_pk_mul_f32 v[112:113], v[112:113], v[8:9] op_sel_hi:[1,0]
	v_pk_mul_f32 v[114:115], v[114:115], v[8:9] op_sel_hi:[1,0]
	v_pk_mul_f32 v[120:121], v[120:121], v[8:9] op_sel_hi:[1,0]
	v_pk_mul_f32 v[122:123], v[122:123], v[8:9] op_sel_hi:[1,0]
	v_pk_mul_f32 v[4:5], v[4:5], v[8:9] op_sel_hi:[1,0]
	v_pk_mul_f32 v[6:7], v[6:7], v[8:9] op_sel_hi:[1,0]
	s_branch .Latt_c_s0
.Latt_rare_s1:
	s_nop 7
	v_cmp_lt_f32_e32 vcc, s44, v40
	s_cbranch_vccz .Latt_r1chk_s1
.Latt_r0_s1:
	v_xor_b32_e32 v10, 16, v237
	v_lshlrev_b32_e32 v10, 2, v10
	ds_bpermute_b32 v10, v10, v40
	v_xor_b32_e32 v43, 32, v237
	v_lshlrev_b32_e32 v43, 2, v43
	v_max_f32_e32 v11, v40, v40
	s_waitcnt lgkmcnt(0)
	v_max_f32_e32 v10, v10, v10
	v_max_f32_e32 v11, v11, v10
	s_nop 0
	ds_bpermute_b32 v10, v43, v11
	s_waitcnt lgkmcnt(0)
	v_max_f32_e32 v10, v10, v10
	v_max_f32_e32 v11, v11, v10
	v_exp_f32_e64 v8, -v11
	v_add_f32_e32 v221, v221, v11
	v_xor_b32_e32 v226, 0x80000000, v221
	v_sub_f32_e32 v148, v148, v11
	v_sub_f32_e32 v149, v149, v11
	v_sub_f32_e32 v150, v150, v11
	v_sub_f32_e32 v151, v151, v11
	v_sub_f32_e32 v152, v152, v11
	v_sub_f32_e32 v153, v153, v11
	v_sub_f32_e32 v154, v154, v11
	v_sub_f32_e32 v155, v155, v11
	v_mov_b32_e32 v227, v226
	v_mov_b32_e32 v228, v226
	v_mov_b32_e32 v229, v226
	v_pk_mul_f32 v[92:93], v[92:93], v[8:9] op_sel_hi:[1,0]
	v_pk_mul_f32 v[94:95], v[94:95], v[8:9] op_sel_hi:[1,0]
	v_pk_mul_f32 v[100:101], v[100:101], v[8:9] op_sel_hi:[1,0]
	v_pk_mul_f32 v[102:103], v[102:103], v[8:9] op_sel_hi:[1,0]
	v_pk_mul_f32 v[108:109], v[108:109], v[8:9] op_sel_hi:[1,0]
	v_pk_mul_f32 v[110:111], v[110:111], v[8:9] op_sel_hi:[1,0]
	v_pk_mul_f32 v[116:117], v[116:117], v[8:9] op_sel_hi:[1,0]
	v_pk_mul_f32 v[118:119], v[118:119], v[8:9] op_sel_hi:[1,0]
	v_pk_mul_f32 v[0:1], v[0:1], v[8:9] op_sel_hi:[1,0]
	v_pk_mul_f32 v[2:3], v[2:3], v[8:9] op_sel_hi:[1,0]
.Latt_r1chk_s1:
	v_cmp_lt_f32_e32 vcc, s44, v42
	s_cbranch_vccz .Latt_c_s1
.Latt_r1_s1:
	v_xor_b32_e32 v10, 16, v237
	v_lshlrev_b32_e32 v10, 2, v10
	ds_bpermute_b32 v10, v10, v42
	v_xor_b32_e32 v43, 32, v237
	v_lshlrev_b32_e32 v43, 2, v43
	v_max_f32_e32 v11, v42, v42
	s_waitcnt lgkmcnt(0)
	v_max_f32_e32 v10, v10, v10
	v_max_f32_e32 v11, v11, v10
	s_nop 0
	ds_bpermute_b32 v10, v43, v11
	s_waitcnt lgkmcnt(0)
	v_max_f32_e32 v10, v10, v10
	v_max_f32_e32 v11, v11, v10
	v_exp_f32_e64 v8, -v11
	v_add_f32_e32 v220, v220, v11
	v_xor_b32_e32 v230, 0x80000000, v220
	v_sub_f32_e32 v132, v132, v11
	v_sub_f32_e32 v133, v133, v11
	v_sub_f32_e32 v134, v134, v11
	v_sub_f32_e32 v135, v135, v11
	v_sub_f32_e32 v136, v136, v11
	v_sub_f32_e32 v137, v137, v11
	v_sub_f32_e32 v138, v138, v11
	v_sub_f32_e32 v139, v139, v11
	v_mov_b32_e32 v231, v230
	v_mov_b32_e32 v232, v230
	v_mov_b32_e32 v233, v230
	v_pk_mul_f32 v[96:97], v[96:97], v[8:9] op_sel_hi:[1,0]
	v_pk_mul_f32 v[98:99], v[98:99], v[8:9] op_sel_hi:[1,0]
	v_pk_mul_f32 v[104:105], v[104:105], v[8:9] op_sel_hi:[1,0]
	v_pk_mul_f32 v[106:107], v[106:107], v[8:9] op_sel_hi:[1,0]
	v_pk_mul_f32 v[112:113], v[112:113], v[8:9] op_sel_hi:[1,0]
	v_pk_mul_f32 v[114:115], v[114:115], v[8:9] op_sel_hi:[1,0]
	v_pk_mul_f32 v[120:121], v[120:121], v[8:9] op_sel_hi:[1,0]
	v_pk_mul_f32 v[122:123], v[122:123], v[8:9] op_sel_hi:[1,0]
	v_pk_mul_f32 v[4:5], v[4:5], v[8:9] op_sel_hi:[1,0]
	v_pk_mul_f32 v[6:7], v[6:7], v[8:9] op_sel_hi:[1,0]
	s_branch .Latt_c_s1

; DEV unsigned pk_bf16(float lo, float hi) { unsigned r; asm("v_cvt_pk_bf16_f32 %0, %1, %2" : "=v"(r) : "v"(lo), "v"(hi)); return r; }
; #define PVLOAD(slot) { const char* s = smem + (slot) * VB; \
;     _Pragma("unroll") for (int vt = 0; vt < 4; ++vt) vf[0][vt] = *(const bf16x8*)(s + vt * 2048 + vro + (((0 * 4 + lq) ^ (l15 >> 1)) << 4)); }
; #define ABAR() { asm volatile("s_waitcnt lgkmcnt(0)" ::: "memory"); __builtin_amdgcn_s_barrier(); asm volatile("" ::: "memory"); }
; DEV void attn_item(const P& p, int bh, int qrow0, int nkt, int outrow0, char* smem) {
;     ...
;   if (skew) { const int sp = (s0 == 0) ? 5 : s0 - 1; PVLOAD(sp); SM(false); PVMMA(sp); }
;   ABAR();
;     ...
;   const int h = bh & 7;
; #pragma unroll
;   for (int qt = 0; qt < 2; ++qt) {
;     const float inv = 1.0f / osum[qt][0];
;     const int row = outrow0 + wid * 32 + qt * 16 + l15;
; #pragma unroll
;     for (int vt = 0; vt < 4; ++vt) {
;       const f32x4 v = o[vt][qt] * inv;
;       *(u32x2*)(Z + (size_t)row * LDZ + ZAO + h * 64 + vt * 16 + lq * 4) = (u32x2){pk_bf16(v[0], v[1]), pk_bf16(v[2], v[3])};
.Latt_exit:
	s_waitcnt lgkmcnt(0)
	v_mfma_f32_16x16x32_bf16 v[92:95], v[16:19], v[148:151], v[92:95]
	v_mfma_f32_16x16x32_bf16 v[96:99], v[16:19], v[132:135], v[96:99]
	v_mfma_f32_16x16x32_bf16 v[100:103], v[20:23], v[148:151], v[100:103]
	v_mfma_f32_16x16x32_bf16 v[104:107], v[20:23], v[132:135], v[104:107]
	v_mfma_f32_16x16x32_bf16 v[108:111], v[24:27], v[148:151], v[108:111]
	v_mfma_f32_16x16x32_bf16 v[112:115], v[24:27], v[132:135], v[112:115]
	v_mfma_f32_16x16x32_bf16 v[116:119], v[28:31], v[148:151], v[116:119]
	v_mfma_f32_16x16x32_bf16 v[120:123], v[28:31], v[132:135], v[120:123]
	v_mfma_f32_16x16x32_bf16 v[0:3], v[222:225], v[148:151], v[0:3]
	v_mfma_f32_16x16x32_bf16 v[4:7], v[222:225], v[132:135], v[4:7]
	s_nop 7
	s_nop 1
	v_mov_b64_e32 v[176:177], v[92:93]
	v_mov_b64_e32 v[178:179], v[94:95]
	v_mov_b64_e32 v[172:173], v[100:101]
	v_mov_b64_e32 v[174:175], v[102:103]
	v_mov_b64_e32 v[168:169], v[108:109]
	v_mov_b64_e32 v[170:171], v[110:111]
	v_mov_b64_e32 v[164:165], v[116:117]
	v_mov_b64_e32 v[166:167], v[118:119]
	v_mov_b64_e32 v[160:161], v[96:97]
	v_mov_b64_e32 v[162:163], v[98:99]
	v_mov_b64_e32 v[156:157], v[104:105]
	v_mov_b64_e32 v[158:159], v[106:107]
	v_mov_b64_e32 v[36:37], v[112:113]
	v_mov_b64_e32 v[38:39], v[114:115]
	v_mov_b64_e32 v[32:33], v[120:121]
	v_mov_b64_e32 v[34:35], v[122:123]
	v_mov_b64_e32 v[22:23], v[4:5]
	v_mov_b64_e32 v[24:25], v[6:7]
	s_branch .LBB0_149
